# previous bundle plus dead-code removal: 18 VALU instructions whose results are never read (lane-address arithmetic of the former ds_bpermute exchanges in the attention loop, leftover address math)
# speedup vs baseline: 1.0099x; 1.0028x over previous
.Lrope_82:
	v_ashrrev_i32_e32 v6, 4, v13
	v_readlane_b32 s72, v241, 17
	v_readlane_b32 s76, v241, 21
	v_readlane_b32 s77, v241, 22
	s_brev_b32 s0, 18
	v_readlane_b32 s73, v241, 18
	v_mov_b32_e32 v2, v190
	v_mov_b32_e32 v190, v191
	v_mov_b32_e32 v191, v192
	v_mov_b32_e32 v192, v193
	v_readlane_b32 s74, v241, 19
	v_readlane_b32 s75, v241, 20
	v_readlane_b32 s78, v241, 23
	v_readlane_b32 s79, v241, 24
	v_readlane_b32 s80, v241, 25
	v_readlane_b32 s81, v241, 26
	v_readlane_b32 s82, v241, 27
	v_readlane_b32 s83, v241, 28
	v_readlane_b32 s84, v241, 29
	v_readlane_b32 s85, v241, 30
	v_readlane_b32 s86, v241, 31
	v_readlane_b32 s87, v241, 32
	v_cvt_f64_i32_e32 v[14:15], v2
	v_mul_f64 v[14:15], v[4:5], v[14:15]
	v_mul_f64 v[16:17], v[14:15], s[68:69]
	v_rndne_f64_e32 v[16:17], v[16:17]
	v_fmac_f64_e32 v[14:15], s[70:71], v[16:17]
	v_cvt_f32_f64_e32 v7, v[14:15]
	v_and_b32_e32 v14, 0x7fffffff, v7
	v_cmp_nlt_f32_e64 s[0:1], |v7|, s0
	s_and_saveexec_b64 s[4:5], s[0:1]
	s_xor_b64 s[76:77], exec, s[4:5]
	s_cbranch_execz .Lrope_84
	v_lshrrev_b32_e32 v2, 23, v14
	v_add_u32_e32 v2, 0xffffff88, v2
	v_cmp_lt_u32_e32 vcc, 63, v2
	s_mov_b32 s3, 0xfe5163ab
	s_nop 0
	v_cndmask_b32_e32 v15, 0, v10, vcc
	v_add_u32_e32 v2, v15, v2
	v_cmp_lt_u32_e64 s[0:1], 31, v2
	s_nop 1
	v_cndmask_b32_e64 v15, 0, v11, s[0:1]
	v_add_u32_e32 v2, v15, v2
	v_cmp_lt_u32_e64 s[4:5], 31, v2
	s_nop 1
	v_cndmask_b32_e64 v15, 0, v11, s[4:5]
	v_add_u32_e32 v15, v15, v2
	v_and_b32_e32 v2, 0x7fffff, v14
	v_or_b32_e32 v28, 0x800000, v2
	v_mad_u64_u32 v[16:17], s[6:7], v28, s3, 0
	v_mov_b32_e32 v2, v17
	s_mov_b32 s3, 0x3c439041
	v_mad_u64_u32 v[18:19], s[6:7], v28, s3, v[2:3]
	v_mov_b32_e32 v2, v19
	s_mov_b32 s3, 0xdb629599
	v_mad_u64_u32 v[20:21], s[6:7], v28, s3, v[2:3]
	v_mov_b32_e32 v2, v21
	s_mov_b32 s3, 0xf534ddc0
	v_mad_u64_u32 v[22:23], s[6:7], v28, s3, v[2:3]
	v_mov_b32_e32 v2, v23
	s_mov_b32 s3, 0xfc2757d1
	v_mad_u64_u32 v[24:25], s[6:7], v28, s3, v[2:3]
	v_mov_b32_e32 v2, v25
	s_mov_b32 s3, 0x4e441529
	v_mad_u64_u32 v[26:27], s[6:7], v28, s3, v[2:3]
	v_mov_b32_e32 v2, v27
	s_mov_b32 s3, 0xa2f9836e
	v_mad_u64_u32 v[28:29], s[6:7], v28, s3, v[2:3]
	v_cndmask_b32_e32 v17, v26, v22, vcc
	v_cndmask_b32_e32 v2, v28, v24, vcc
	v_cndmask_b32_e32 v21, v29, v26, vcc
	v_cndmask_b32_e64 v19, v2, v17, s[0:1]
	v_cndmask_b32_e64 v2, v21, v2, s[0:1]
	v_cndmask_b32_e32 v21, v24, v20, vcc
	v_cndmask_b32_e64 v17, v17, v21, s[0:1]
	v_cndmask_b32_e64 v2, v2, v19, s[4:5]
	v_cndmask_b32_e64 v19, v19, v17, s[4:5]
	v_sub_u32_e32 v23, 32, v15
	v_alignbit_b32 v24, v2, v19, v23
	v_cmp_eq_u32_e64 s[6:7], 0, v15
	v_cndmask_b32_e32 v16, v20, v16, vcc
	s_nop 0
	v_cndmask_b32_e64 v15, v24, v2, s[6:7]
	v_cndmask_b32_e32 v2, v22, v18, vcc
	v_cndmask_b32_e64 v18, v21, v2, s[0:1]
	v_cndmask_b32_e64 v17, v17, v18, s[4:5]
	v_alignbit_b32 v21, v19, v17, v23
	v_cndmask_b32_e64 v19, v21, v19, s[6:7]
	v_bfe_u32 v24, v15, 29, 1
	v_cndmask_b32_e64 v2, v2, v16, s[0:1]
	v_alignbit_b32 v21, v15, v19, 30
	v_sub_u32_e32 v25, 0, v24
	v_cndmask_b32_e64 v2, v18, v2, s[4:5]
	v_xor_b32_e32 v21, v21, v25
	v_alignbit_b32 v16, v17, v2, v23
	v_cndmask_b32_e64 v16, v16, v17, s[6:7]
	v_ffbh_u32_e32 v18, v21
	v_alignbit_b32 v17, v19, v16, 30
	v_min_u32_e32 v18, 32, v18
	v_alignbit_b32 v2, v16, v2, 30
	v_xor_b32_e32 v17, v17, v25
	v_sub_u32_e32 v19, 31, v18
	v_xor_b32_e32 v2, v2, v25
	v_alignbit_b32 v20, v21, v17, v19
	v_alignbit_b32 v2, v17, v2, v19
	v_alignbit_b32 v16, v20, v2, 9
	v_ffbh_u32_e32 v17, v16
	v_min_u32_e32 v17, 32, v17
	v_lshrrev_b32_e32 v22, 29, v15
	v_not_b32_e32 v19, v17
	v_alignbit_b32 v2, v16, v2, v19
	v_lshlrev_b32_e32 v16, 31, v22
	v_or_b32_e32 v19, 0x33000000, v16
	v_add_lshl_u32 v17, v17, v18, 23
	v_lshrrev_b32_e32 v2, 9, v2
	v_sub_u32_e32 v17, v19, v17
	v_or_b32_e32 v16, 0.5, v16
	v_lshlrev_b32_e32 v18, 23, v18
	v_or_b32_e32 v2, v17, v2
	v_lshrrev_b32_e32 v17, 9, v20
	v_sub_u32_e32 v16, v16, v18
	v_or_b32_e32 v16, v17, v16
	v_mul_f32_e32 v17, 0x3fc90fda, v16
	s_mov_b32 s0, 0x3fc90fda
	v_fma_f32 v18, v16, s0, -v17
	v_fmac_f32_e32 v18, 0x33a22168, v16
	v_fmac_f32_e32 v18, 0x3fc90fda, v2
	v_lshrrev_b32_e32 v15, 30, v15
	v_add_f32_e32 v2, v17, v18
	v_add_u32_e32 v15, v24, v15

.LBB0_997:
	s_or_b64 exec, exec, s[0:1]
	s_waitcnt lgkmcnt(0)
	s_cmpk_gt_i32 s90, 0xff
	s_barrier
	s_cbranch_scc1 .LBB0_1034
	s_mov_b32 s73, s90
	s_cmp_lg_u32 s88, 0x100
	s_cbranch_scc1 .Lscan_noremap
	s_and_b32 s73, s90, 7
	s_lshl_b32 s73, s73, 5
	s_lshr_b32 s2, s90, 3
	s_or_b32 s73, s73, s2

.LBB0_1046:
	s_or_b64 exec, exec, s[22:23]
	global_load_dwordx4 v[152:155], v[168:169], off
	s_and_b32 s25, s4, 1
	v_cmp_le_i32_e32 vcc, s4, v185
	s_and_saveexec_b64 s[22:23], vcc
	s_cbranch_execz .LBB0_1052
	s_mul_i32 s26, s25, 0x5600
	s_add_i32 s26, s26, 0
	v_add3_u32 v187, s26, v184, v166
	ds_read_b128 v[64:67], v187
	ds_read_b128 v[188:191], v187 offset:32
	s_waitcnt lgkmcnt(1)
	v_mfma_f32_32x32x16_bf16 v[80:95], v[64:67], v[132:135], 0
	v_mfma_f32_32x32x16_bf16 v[64:79], v[64:67], v[140:143], 0
	s_waitcnt lgkmcnt(0)
	v_mfma_f32_32x32x16_bf16 v[80:95], v[188:191], v[124:127], v[80:95]
	v_mfma_f32_32x32x16_bf16 v[64:79], v[188:191], v[136:139], v[64:79]
	ds_read_b128 v[188:191], v187 offset:64
	ds_read_b128 v[192:195], v187 offset:96
	s_waitcnt lgkmcnt(1)
	v_mfma_f32_32x32x16_bf16 v[80:95], v[188:191], v[120:123], v[80:95]
	s_waitcnt lgkmcnt(0)
	v_mfma_f32_32x32x16_bf16 v[80:95], v[192:195], v[116:119], v[80:95]
	v_mfma_f32_32x32x16_bf16 v[64:79], v[188:191], v[128:131], v[64:79]
	ds_read_b128 v[188:191], v187 offset:128
	ds_read_b128 v[196:199], v187 offset:160
	s_nop 1
	s_waitcnt lgkmcnt(1)
	v_mfma_f32_32x32x16_bf16 v[80:95], v[188:191], v[112:115], v[80:95]
	s_waitcnt lgkmcnt(0)
	v_mfma_f32_32x32x16_bf16 v[80:95], v[196:199], v[108:111], v[80:95]
	v_mfma_f32_32x32x16_bf16 v[64:79], v[192:195], v[104:107], v[64:79]
	s_nop 10
	v_max_f32_e32 v200, v81, v81
	v_max_f32_e32 v192, v80, v80
	v_max_f32_e32 v192, v192, v200
	v_max3_f32 v192, v192, v82, v83
	v_max3_f32 v192, v192, v84, v85
	v_max3_f32 v192, v192, v86, v87
	v_max3_f32 v192, v192, v88, v89
	v_mfma_f32_32x32x16_bf16 v[64:79], v[188:191], v[100:103], v[64:79]
	v_max3_f32 v192, v192, v90, v91
	v_max3_f32 v188, v192, v92, v93
	v_max3_f32 v188, v188, v94, v95
	v_mov_b32_e32 v189, v188
	s_nop 1
	v_permlane32_swap_b32_e32 v189, v188
	s_waitcnt lgkmcnt(0)
	v_max_f32_e32 v189, v189, v189
	v_mfma_f32_32x32x16_bf16 v[64:79], v[196:199], v[96:99], v[64:79]
	v_max_f32_e32 v188, v188, v189
	v_add_f32_e32 v189, 0x41000000, v161
	v_cmp_gt_f32_e32 vcc, v188, v189
	s_cbranch_vccz .LBB0_1049
	v_max_f32_e32 v188, v188, v188
	v_max_f32_e32 v189, v161, v161
	v_max_f32_e32 v189, v189, v188
	v_sub_f32_e32 v161, v161, v189
	v_exp_f32_e32 v188, v161
	v_mov_b32_e32 v161, v189
	v_mul_f32_e32 v162, v162, v188
	v_pk_mul_f32 v[62:63], v[62:63], v[188:189] op_sel_hi:[1,0]
	v_pk_mul_f32 v[60:61], v[60:61], v[188:189] op_sel_hi:[1,0]
	v_pk_mul_f32 v[58:59], v[58:59], v[188:189] op_sel_hi:[1,0]
	v_pk_mul_f32 v[56:57], v[56:57], v[188:189] op_sel_hi:[1,0]
	v_pk_mul_f32 v[54:55], v[54:55], v[188:189] op_sel_hi:[1,0]
	v_pk_mul_f32 v[52:53], v[52:53], v[188:189] op_sel_hi:[1,0]
	v_pk_mul_f32 v[50:51], v[50:51], v[188:189] op_sel_hi:[1,0]
	v_pk_mul_f32 v[48:49], v[48:49], v[188:189] op_sel_hi:[1,0]
	v_pk_mul_f32 v[46:47], v[46:47], v[188:189] op_sel_hi:[1,0]
	v_pk_mul_f32 v[44:45], v[44:45], v[188:189] op_sel_hi:[1,0]
	v_pk_mul_f32 v[42:43], v[42:43], v[188:189] op_sel_hi:[1,0]
	v_pk_mul_f32 v[40:41], v[40:41], v[188:189] op_sel_hi:[1,0]
	v_pk_mul_f32 v[38:39], v[38:39], v[188:189] op_sel_hi:[1,0]
	v_pk_mul_f32 v[36:37], v[36:37], v[188:189] op_sel_hi:[1,0]
	v_pk_mul_f32 v[34:35], v[34:35], v[188:189] op_sel_hi:[1,0]
	v_pk_mul_f32 v[32:33], v[32:33], v[188:189] op_sel_hi:[1,0]

.LBB0_1054:
	v_cmp_lt_i32_e32 vcc, 2, v163
	s_and_saveexec_b64 s[0:1], vcc
	s_cbranch_execz .LBB0_1060
	s_bitcmp1_b32 s24, 0
	s_cselect_b32 s4, 0x5600, 0
	s_add_i32 s4, s4, 0
	v_add3_u32 v148, s4, v184, v166
	ds_read_b128 v[64:67], v148
	ds_read_b128 v[144:147], v148 offset:32
	s_waitcnt lgkmcnt(1)
	v_mfma_f32_32x32x16_bf16 v[80:95], v[64:67], v[132:135], 0
	s_waitcnt lgkmcnt(0)
	v_mfma_f32_32x32x16_bf16 v[80:95], v[144:147], v[124:127], v[80:95]
	ds_read_b128 v[124:127], v148 offset:64
	ds_read_b128 v[132:135], v148 offset:96
	s_waitcnt lgkmcnt(1)
	v_mfma_f32_32x32x16_bf16 v[80:95], v[124:127], v[120:123], v[80:95]
	v_mfma_f32_32x32x16_bf16 v[64:79], v[64:67], v[140:143], 0
	s_waitcnt lgkmcnt(0)
	v_mfma_f32_32x32x16_bf16 v[80:95], v[132:135], v[116:119], v[80:95]
	ds_read_b128 v[116:119], v148 offset:128
	ds_read_b128 v[120:123], v148 offset:160
	v_mfma_f32_32x32x16_bf16 v[64:79], v[144:147], v[136:139], v[64:79]
	s_waitcnt lgkmcnt(1)
	v_mfma_f32_32x32x16_bf16 v[80:95], v[116:119], v[112:115], v[80:95]
	v_mfma_f32_32x32x16_bf16 v[64:79], v[124:127], v[128:131], v[64:79]
	s_waitcnt lgkmcnt(0)
	v_mfma_f32_32x32x16_bf16 v[80:95], v[120:123], v[108:111], v[80:95]
	s_nop 1
	v_mfma_f32_32x32x16_bf16 v[64:79], v[132:135], v[104:107], v[64:79]
	s_nop 3
	s_nop 1
	s_nop 2
	v_max_f32_e32 v109, v81, v81
	v_max_f32_e32 v104, v80, v80
	v_max_f32_e32 v104, v104, v109
	v_max3_f32 v104, v104, v82, v83
	v_max3_f32 v104, v104, v84, v85
	v_max3_f32 v104, v104, v86, v87
	v_max3_f32 v104, v104, v88, v89
	v_mfma_f32_32x32x16_bf16 v[64:79], v[116:119], v[100:103], v[64:79]
	v_max3_f32 v104, v104, v90, v91
	v_max3_f32 v100, v104, v92, v93
	v_max3_f32 v100, v100, v94, v95
	v_mov_b32_e32 v101, v100
	s_nop 1
	v_permlane32_swap_b32_e32 v101, v100
	s_waitcnt lgkmcnt(0)
	v_max_f32_e32 v101, v101, v101
	v_mfma_f32_32x32x16_bf16 v[64:79], v[120:123], v[96:99], v[64:79]
	v_max_f32_e32 v100, v100, v101
	v_add_f32_e32 v101, 0x41000000, v161
	v_cmp_gt_f32_e32 vcc, v100, v101
	s_cbranch_vccz .LBB0_1057
	v_max_f32_e32 v96, v100, v100
	v_max_f32_e32 v97, v161, v161
	v_max_f32_e32 v97, v97, v96
	v_sub_f32_e32 v96, v161, v97
	v_exp_f32_e32 v96, v96
	v_mov_b32_e32 v161, v97
	v_mul_f32_e32 v162, v162, v96
	v_pk_mul_f32 v[62:63], v[62:63], v[96:97] op_sel_hi:[1,0]
	v_pk_mul_f32 v[60:61], v[60:61], v[96:97] op_sel_hi:[1,0]
	v_pk_mul_f32 v[58:59], v[58:59], v[96:97] op_sel_hi:[1,0]
	v_pk_mul_f32 v[56:57], v[56:57], v[96:97] op_sel_hi:[1,0]
	v_pk_mul_f32 v[54:55], v[54:55], v[96:97] op_sel_hi:[1,0]
	v_pk_mul_f32 v[52:53], v[52:53], v[96:97] op_sel_hi:[1,0]
	v_pk_mul_f32 v[50:51], v[50:51], v[96:97] op_sel_hi:[1,0]
	v_pk_mul_f32 v[48:49], v[48:49], v[96:97] op_sel_hi:[1,0]
	v_pk_mul_f32 v[46:47], v[46:47], v[96:97] op_sel_hi:[1,0]
	v_pk_mul_f32 v[44:45], v[44:45], v[96:97] op_sel_hi:[1,0]
	v_pk_mul_f32 v[42:43], v[42:43], v[96:97] op_sel_hi:[1,0]
	v_pk_mul_f32 v[40:41], v[40:41], v[96:97] op_sel_hi:[1,0]
	v_pk_mul_f32 v[38:39], v[38:39], v[96:97] op_sel_hi:[1,0]
	v_pk_mul_f32 v[36:37], v[36:37], v[96:97] op_sel_hi:[1,0]
	v_pk_mul_f32 v[34:35], v[34:35], v[96:97] op_sel_hi:[1,0]
	v_pk_mul_f32 v[32:33], v[32:33], v[96:97] op_sel_hi:[1,0]

.LBB0_1062:
	s_or_b64 exec, exec, s[22:23]
	s_waitcnt lgkmcnt(0)
	s_barrier
	s_and_saveexec_b64 s[0:1], vcc
	s_cbranch_execz .LBB0_1035
	s_lshl_b32 s4, s41, 9
	s_and_b32 s4, s4, 0x7000
	s_add_i32 s4, s4, s55
	v_readlane_b32 s68, v240, 1
	v_lshl_add_u64 v[64:65], v[164:165], 0, s[4:5]
	v_readlane_b32 s74, v240, 7
	v_readlane_b32 s75, v240, 8
	v_or_b32_e32 v64, v64, v159
	s_lshl_b32 s4, s41, 7
	v_mov_b64_e32 v[66:67], s[74:75]
	v_mad_u64_u32 v[68:69], s[22:23], v64, s39, v[66:67]
	v_mad_i32_i24 v69, v65, s39, v69
	s_and_b32 s4, s4, 0x380
	v_lshl_add_u64 v[68:69], v[68:69], 0, s[4:5]
	v_mov_b32_e32 v159, v157
	v_lshl_add_u64 v[68:69], v[68:69], 0, v[158:159]
	global_load_dwordx2 v[176:177], v[68:69], off
	global_load_dwordx2 v[178:179], v[68:69], off offset:16
	global_load_dwordx2 v[180:181], v[68:69], off offset:32
	global_load_dwordx2 v[182:183], v[68:69], off offset:48
	global_load_dwordx2 v[184:185], v[68:69], off offset:64
	global_load_dwordx2 v[186:187], v[68:69], off offset:80
	global_load_dwordx2 v[188:189], v[68:69], off offset:96
	global_load_dwordx2 v[190:191], v[68:69], off offset:112
	s_mov_b32 s98, 0x30000
	s_mov_b32 s99, 0
	v_lshl_add_u64 v[208:209], v[68:69], 0, s[98:99]
	global_load_dwordx2 v[192:193], v[208:209], off
	global_load_dwordx2 v[194:195], v[208:209], off offset:16
	global_load_dwordx2 v[196:197], v[208:209], off offset:32
	global_load_dwordx2 v[198:199], v[208:209], off offset:48
	global_load_dwordx2 v[200:201], v[208:209], off offset:64
	global_load_dwordx2 v[202:203], v[208:209], off offset:80
	global_load_dwordx2 v[204:205], v[208:209], off offset:96
	global_load_dwordx2 v[206:207], v[208:209], off offset:112
	ds_read2st64_b32 v[78:79], v83 offset1:1
	v_max_f32_e32 v86, v161, v161
	ds_read2st64_b32 v[72:73], v82 offset1:1
	ds_read2st64_b32 v[74:75], v82 offset0:2 offset1:3
	ds_read2st64_b32 v[76:77], v82 offset0:4 offset1:5
	ds_read2st64_b32 v[80:81], v82 offset0:6 offset1:7
	ds_read2st64_b32 v[84:85], v83 offset0:2 offset1:3
	v_readlane_b32 s76, v240, 9
	v_readlane_b32 s77, v240, 10
	s_waitcnt lgkmcnt(5)
	v_max_f32_e32 v83, v78, v78
	v_mov_b32_e32 v163, v79
	v_max_f32_e32 v79, v86, v83
	v_sub_f32_e32 v83, v161, v79
	v_sub_f32_e32 v79, v78, v79
	v_exp_f32_e32 v78, v83
	v_exp_f32_e32 v79, v79
	v_readlane_b32 s78, v240, 11
	v_readlane_b32 s79, v240, 12
	v_readlane_b32 s80, v240, 13
	v_pk_mul_f32 v[88:89], v[162:163], v[78:79]
	v_readlane_b32 s81, v240, 14
	v_add_f32_e32 v83, v88, v89
	v_div_scale_f32 v88, s[22:23], v83, v83, 1.0
	v_rcp_f32_e32 v89, v88
	v_div_scale_f32 v90, vcc, 1.0, v83, 1.0
	v_readlane_b32 s82, v240, 15
	v_fma_f32 v91, -v88, v89, 1.0
	v_fmac_f32_e32 v89, v91, v89
	v_mul_f32_e32 v91, v90, v89
	v_fma_f32 v92, -v88, v91, v90
	v_fmac_f32_e32 v91, v92, v89
	v_fma_f32 v88, -v88, v91, v90
	v_div_fmas_f32 v88, v88, v89, v91
	v_div_fixup_f32 v83, v88, v83, 1.0
	v_readlane_b32 s83, v240, 16
	s_mov_b64 s[44:45], s[76:77]
	v_mul_f32_e32 v88, v79, v83
	s_mov_b64 s[50:51], s[82:83]
	v_lshlrev_b64 v[86:87], 11, v[64:65]
	v_mul_f32_e32 v78, v78, v83
	s_waitcnt lgkmcnt(4)
	v_pk_mul_f32 v[72:73], v[72:73], v[88:89] op_sel_hi:[1,0]
	s_waitcnt lgkmcnt(3)
	v_pk_mul_f32 v[74:75], v[74:75], v[88:89] op_sel_hi:[1,0]
	v_lshl_add_u64 v[86:87], s[50:51], 0, v[86:87]
	v_pk_fma_f32 v[48:49], v[48:49], v[78:79], v[72:73] op_sel_hi:[1,0,1]
	v_pk_fma_f32 v[50:51], v[50:51], v[78:79], v[74:75] op_sel_hi:[1,0,1]
	v_lshl_add_u64 v[86:87], v[86:87], 0, s[4:5]
	v_lshl_add_u64 v[86:87], v[86:87], 0, v[158:159]
	v_or_b32_e32 v64, 32, v64
	s_waitcnt lgkmcnt(0)
	v_mov_b32_e32 v161, v85
	v_readlane_b32 s69, v240, 2
	v_readlane_b32 s70, v240, 3
	v_readlane_b32 s71, v240, 4
	v_readlane_b32 s72, v240, 5
	v_readlane_b32 s73, v240, 6
	s_mov_b64 s[46:47], s[78:79]
	s_mov_b64 s[48:49], s[80:81]
	s_waitcnt vmcnt(15)
	v_mov_b32_e32 v70, v176
	v_mov_b32_e32 v71, v177
	v_lshlrev_b32_e32 v72, 16, v70
	v_and_b32_e32 v73, 0xffff0000, v70
	v_lshlrev_b32_e32 v70, 16, v71
	v_and_b32_e32 v71, 0xffff0000, v71
	v_pk_mul_f32 v[48:49], v[48:49], v[72:73]
	v_pk_mul_f32 v[50:51], v[50:51], v[70:71]
	v_cvt_pk_bf16_f32 v48, v48, v49
	v_cvt_pk_bf16_f32 v49, v50, v51
	global_store_dwordx2 v[86:87], v[48:49], off
	v_pk_mul_f32 v[50:51], v[88:89], v[76:77] op_sel_hi:[0,1]
	v_pk_mul_f32 v[70:71], v[88:89], v[80:81] op_sel_hi:[0,1]
	v_pk_fma_f32 v[50:51], v[52:53], v[78:79], v[50:51] op_sel_hi:[1,0,1]
	v_pk_fma_f32 v[52:53], v[54:55], v[78:79], v[70:71] op_sel_hi:[1,0,1]
	s_waitcnt vmcnt(15)
	v_mov_b32_e32 v48, v178
	v_mov_b32_e32 v49, v179
	v_lshlrev_b32_e32 v54, 16, v48
	v_and_b32_e32 v55, 0xffff0000, v48
	v_lshlrev_b32_e32 v48, 16, v49
	v_and_b32_e32 v49, 0xffff0000, v49
	v_pk_mul_f32 v[50:51], v[50:51], v[54:55]
	v_pk_mul_f32 v[48:49], v[52:53], v[48:49]
	v_cvt_pk_bf16_f32 v50, v50, v51
	v_cvt_pk_bf16_f32 v51, v48, v49
	global_store_dwordx2 v[86:87], v[50:51], off offset:16
	ds_read2st64_b32 v[50:51], v82 offset0:8 offset1:9
	ds_read2st64_b32 v[52:53], v82 offset0:10 offset1:11
	ds_read2st64_b32 v[54:55], v82 offset0:12 offset1:13
	ds_read2st64_b32 v[70:71], v82 offset0:14 offset1:15
	s_waitcnt lgkmcnt(3)
	v_pk_mul_f32 v[50:51], v[88:89], v[50:51] op_sel_hi:[0,1]
	s_waitcnt lgkmcnt(2)
	v_pk_mul_f32 v[52:53], v[88:89], v[52:53] op_sel_hi:[0,1]
	v_pk_fma_f32 v[50:51], v[56:57], v[78:79], v[50:51] op_sel_hi:[1,0,1]
	v_pk_fma_f32 v[52:53], v[58:59], v[78:79], v[52:53] op_sel_hi:[1,0,1]
	s_waitcnt vmcnt(15)
	v_mov_b32_e32 v48, v180
	v_mov_b32_e32 v49, v181
	v_lshlrev_b32_e32 v56, 16, v48
	v_and_b32_e32 v57, 0xffff0000, v48
	v_lshlrev_b32_e32 v48, 16, v49
	v_and_b32_e32 v49, 0xffff0000, v49
	v_pk_mul_f32 v[50:51], v[50:51], v[56:57]
	v_pk_mul_f32 v[48:49], v[52:53], v[48:49]
	v_cvt_pk_bf16_f32 v50, v50, v51
	v_cvt_pk_bf16_f32 v51, v48, v49
	global_store_dwordx2 v[86:87], v[50:51], off offset:32
	s_waitcnt lgkmcnt(1)
	v_pk_mul_f32 v[50:51], v[88:89], v[54:55] op_sel_hi:[0,1]
	s_waitcnt lgkmcnt(0)
	v_pk_mul_f32 v[52:53], v[88:89], v[70:71] op_sel_hi:[0,1]
	v_pk_fma_f32 v[50:51], v[60:61], v[78:79], v[50:51] op_sel_hi:[1,0,1]
	v_pk_fma_f32 v[52:53], v[62:63], v[78:79], v[52:53] op_sel_hi:[1,0,1]
	s_waitcnt vmcnt(15)
	v_mov_b32_e32 v48, v182
	v_mov_b32_e32 v49, v183
	v_lshlrev_b32_e32 v54, 16, v48
	v_and_b32_e32 v55, 0xffff0000, v48
	v_lshlrev_b32_e32 v48, 16, v49
	v_and_b32_e32 v49, 0xffff0000, v49
	v_pk_mul_f32 v[50:51], v[50:51], v[54:55]
	v_pk_mul_f32 v[48:49], v[52:53], v[48:49]
	v_cvt_pk_bf16_f32 v50, v50, v51
	v_cvt_pk_bf16_f32 v51, v48, v49
	global_store_dwordx2 v[86:87], v[50:51], off offset:48
	ds_read2st64_b32 v[50:51], v82 offset0:16 offset1:17
	ds_read2st64_b32 v[52:53], v82 offset0:18 offset1:19
	ds_read2st64_b32 v[54:55], v82 offset0:20 offset1:21
	ds_read2st64_b32 v[56:57], v82 offset0:22 offset1:23
	s_waitcnt lgkmcnt(3)
	v_pk_mul_f32 v[50:51], v[88:89], v[50:51] op_sel_hi:[0,1]
	s_waitcnt lgkmcnt(2)
	v_pk_mul_f32 v[52:53], v[88:89], v[52:53] op_sel_hi:[0,1]
	v_pk_fma_f32 v[32:33], v[32:33], v[78:79], v[50:51] op_sel_hi:[1,0,1]
	v_pk_fma_f32 v[34:35], v[34:35], v[78:79], v[52:53] op_sel_hi:[1,0,1]
	s_waitcnt vmcnt(15)
	v_mov_b32_e32 v48, v184
	v_mov_b32_e32 v49, v185
	v_lshlrev_b32_e32 v50, 16, v48
	v_and_b32_e32 v51, 0xffff0000, v48
	v_lshlrev_b32_e32 v48, 16, v49
	v_and_b32_e32 v49, 0xffff0000, v49
	v_pk_mul_f32 v[32:33], v[32:33], v[50:51]
	v_pk_mul_f32 v[34:35], v[34:35], v[48:49]
	v_cvt_pk_bf16_f32 v32, v32, v33
	v_cvt_pk_bf16_f32 v33, v34, v35
	global_store_dwordx2 v[86:87], v[32:33], off offset:64
	s_waitcnt lgkmcnt(1)
	v_pk_mul_f32 v[34:35], v[88:89], v[54:55] op_sel_hi:[0,1]
	s_waitcnt lgkmcnt(0)
	v_pk_mul_f32 v[48:49], v[88:89], v[56:57] op_sel_hi:[0,1]
	v_pk_fma_f32 v[34:35], v[36:37], v[78:79], v[34:35] op_sel_hi:[1,0,1]
	v_pk_fma_f32 v[36:37], v[38:39], v[78:79], v[48:49] op_sel_hi:[1,0,1]
	s_waitcnt vmcnt(15)
	v_mov_b32_e32 v32, v186
	v_mov_b32_e32 v33, v187
	v_lshlrev_b32_e32 v38, 16, v32
	v_and_b32_e32 v39, 0xffff0000, v32
	v_lshlrev_b32_e32 v32, 16, v33
	v_and_b32_e32 v33, 0xffff0000, v33
	v_pk_mul_f32 v[34:35], v[34:35], v[38:39]
	v_pk_mul_f32 v[32:33], v[36:37], v[32:33]
	v_cvt_pk_bf16_f32 v34, v34, v35
	v_cvt_pk_bf16_f32 v35, v32, v33
	global_store_dwordx2 v[86:87], v[34:35], off offset:80
	ds_read2st64_b32 v[34:35], v82 offset0:24 offset1:25
	ds_read2st64_b32 v[36:37], v82 offset0:26 offset1:27
	ds_read2st64_b32 v[38:39], v82 offset0:28 offset1:29
	ds_read2st64_b32 v[48:49], v82 offset0:30 offset1:31
	s_waitcnt lgkmcnt(3)
	v_pk_mul_f32 v[34:35], v[88:89], v[34:35] op_sel_hi:[0,1]
	s_waitcnt lgkmcnt(2)
	v_pk_mul_f32 v[36:37], v[88:89], v[36:37] op_sel_hi:[0,1]
	v_pk_fma_f32 v[34:35], v[40:41], v[78:79], v[34:35] op_sel_hi:[1,0,1]
	v_pk_fma_f32 v[36:37], v[42:43], v[78:79], v[36:37] op_sel_hi:[1,0,1]
	s_waitcnt vmcnt(15)
	v_mov_b32_e32 v32, v188
	v_mov_b32_e32 v33, v189
	v_lshlrev_b32_e32 v40, 16, v32
	v_and_b32_e32 v41, 0xffff0000, v32
	v_lshlrev_b32_e32 v32, 16, v33
	v_and_b32_e32 v33, 0xffff0000, v33
	v_pk_mul_f32 v[34:35], v[34:35], v[40:41]
	v_pk_mul_f32 v[32:33], v[36:37], v[32:33]
	v_cvt_pk_bf16_f32 v34, v34, v35
	v_cvt_pk_bf16_f32 v35, v32, v33
	global_store_dwordx2 v[86:87], v[34:35], off offset:96
	s_waitcnt lgkmcnt(1)
	v_pk_mul_f32 v[36:37], v[88:89], v[38:39] op_sel_hi:[0,1]
	s_waitcnt lgkmcnt(0)
	v_pk_mul_f32 v[38:39], v[88:89], v[48:49] op_sel_hi:[0,1]
	v_mad_u64_u32 v[32:33], s[22:23], v64, s39, v[66:67]
	v_pk_fma_f32 v[36:37], v[44:45], v[78:79], v[36:37] op_sel_hi:[1,0,1]
	v_pk_fma_f32 v[38:39], v[46:47], v[78:79], v[38:39] op_sel_hi:[1,0,1]
	s_waitcnt vmcnt(15)
	v_mov_b32_e32 v34, v190
	v_mov_b32_e32 v35, v191
	v_lshlrev_b32_e32 v40, 16, v34
	v_and_b32_e32 v41, 0xffff0000, v34
	v_lshlrev_b32_e32 v34, 16, v35
	v_and_b32_e32 v35, 0xffff0000, v35
	v_pk_mul_f32 v[36:37], v[36:37], v[40:41]
	v_pk_mul_f32 v[34:35], v[38:39], v[34:35]
	v_cvt_pk_bf16_f32 v36, v36, v37
	v_cvt_pk_bf16_f32 v37, v34, v35
	global_store_dwordx2 v[86:87], v[36:37], off offset:112
	v_max_f32_e32 v34, v167, v167
	v_max_f32_e32 v35, v84, v84
	v_max_f32_e32 v34, v34, v35
	v_sub_f32_e32 v35, v167, v34
	v_sub_f32_e32 v34, v84, v34
	v_exp_f32_e32 v36, v35
	v_exp_f32_e32 v37, v34
	ds_read2st64_b32 v[42:43], v82 offset0:32 offset1:33
	ds_read2st64_b32 v[44:45], v82 offset0:34 offset1:35
	ds_read2st64_b32 v[46:47], v82 offset0:36 offset1:37
	ds_read2st64_b32 v[48:49], v82 offset0:38 offset1:39
	v_lshlrev_b64 v[34:35], 11, v[64:65]
	v_lshl_add_u64 v[34:35], s[50:51], 0, v[34:35]
	v_pk_mul_f32 v[38:39], v[160:161], v[36:37]
	v_lshl_add_u64 v[34:35], v[34:35], 0, s[4:5]
	v_add_f32_e32 v38, v38, v39
	v_div_scale_f32 v39, s[22:23], v38, v38, 1.0
	v_rcp_f32_e32 v50, v39
	v_div_scale_f32 v51, vcc, 1.0, v38, 1.0
	v_lshl_add_u64 v[34:35], v[34:35], 0, v[158:159]
	v_fma_f32 v52, -v39, v50, 1.0
	v_fmac_f32_e32 v50, v52, v50
	v_mul_f32_e32 v52, v51, v50
	v_fma_f32 v53, -v39, v52, v51
	v_fmac_f32_e32 v52, v53, v50
	v_fma_f32 v39, -v39, v52, v51
	v_div_fmas_f32 v39, v39, v50, v52
	v_div_fixup_f32 v38, v39, v38, 1.0
	v_mul_f32_e32 v36, v36, v38
	v_mul_f32_e32 v38, v37, v38
	s_waitcnt lgkmcnt(3)
	v_pk_mul_f32 v[42:43], v[42:43], v[38:39] op_sel_hi:[1,0]
	s_waitcnt lgkmcnt(2)
	v_pk_mul_f32 v[44:45], v[44:45], v[38:39] op_sel_hi:[1,0]
	v_pk_fma_f32 v[16:17], v[16:17], v[36:37], v[42:43] op_sel_hi:[1,0,1]
	v_pk_fma_f32 v[18:19], v[18:19], v[36:37], v[44:45] op_sel_hi:[1,0,1]
	s_waitcnt vmcnt(15)
	v_mov_b32_e32 v40, v192
	v_mov_b32_e32 v41, v193
	v_lshlrev_b32_e32 v42, 16, v40
	v_and_b32_e32 v43, 0xffff0000, v40
	v_lshlrev_b32_e32 v40, 16, v41
	v_and_b32_e32 v41, 0xffff0000, v41
	v_pk_mul_f32 v[16:17], v[16:17], v[42:43]
	v_pk_mul_f32 v[18:19], v[18:19], v[40:41]
	v_cvt_pk_bf16_f32 v16, v16, v17
	v_cvt_pk_bf16_f32 v17, v18, v19
	global_store_dwordx2 v[34:35], v[16:17], off
	s_waitcnt lgkmcnt(1)
	v_pk_mul_f32 v[18:19], v[38:39], v[46:47] op_sel_hi:[0,1]
	s_waitcnt lgkmcnt(0)
	v_pk_mul_f32 v[40:41], v[38:39], v[48:49] op_sel_hi:[0,1]
	v_pk_fma_f32 v[18:19], v[20:21], v[36:37], v[18:19] op_sel_hi:[1,0,1]
	v_pk_fma_f32 v[20:21], v[22:23], v[36:37], v[40:41] op_sel_hi:[1,0,1]
	s_waitcnt vmcnt(15)
	v_mov_b32_e32 v16, v194
	v_mov_b32_e32 v17, v195
	v_lshlrev_b32_e32 v22, 16, v16
	v_and_b32_e32 v23, 0xffff0000, v16
	v_lshlrev_b32_e32 v16, 16, v17
	v_and_b32_e32 v17, 0xffff0000, v17
	v_pk_mul_f32 v[18:19], v[18:19], v[22:23]
	v_pk_mul_f32 v[16:17], v[20:21], v[16:17]
	v_cvt_pk_bf16_f32 v18, v18, v19
	v_cvt_pk_bf16_f32 v19, v16, v17
	global_store_dwordx2 v[34:35], v[18:19], off offset:16
	ds_read2st64_b32 v[18:19], v82 offset0:40 offset1:41
	ds_read2st64_b32 v[20:21], v82 offset0:42 offset1:43
	ds_read2st64_b32 v[22:23], v82 offset0:44 offset1:45
	ds_read2st64_b32 v[40:41], v82 offset0:46 offset1:47
	s_waitcnt lgkmcnt(3)
	v_pk_mul_f32 v[18:19], v[38:39], v[18:19] op_sel_hi:[0,1]
	s_waitcnt lgkmcnt(2)
	v_pk_mul_f32 v[20:21], v[38:39], v[20:21] op_sel_hi:[0,1]
	v_pk_fma_f32 v[18:19], v[24:25], v[36:37], v[18:19] op_sel_hi:[1,0,1]
	v_pk_fma_f32 v[20:21], v[26:27], v[36:37], v[20:21] op_sel_hi:[1,0,1]
	s_waitcnt vmcnt(15)
	v_mov_b32_e32 v16, v196
	v_mov_b32_e32 v17, v197
	v_lshlrev_b32_e32 v24, 16, v16
	v_and_b32_e32 v25, 0xffff0000, v16
	v_lshlrev_b32_e32 v16, 16, v17
	v_and_b32_e32 v17, 0xffff0000, v17
	v_pk_mul_f32 v[18:19], v[18:19], v[24:25]
	v_pk_mul_f32 v[16:17], v[20:21], v[16:17]
	v_cvt_pk_bf16_f32 v18, v18, v19
	v_cvt_pk_bf16_f32 v19, v16, v17
	global_store_dwordx2 v[34:35], v[18:19], off offset:32
	s_waitcnt lgkmcnt(1)
	v_pk_mul_f32 v[18:19], v[38:39], v[22:23] op_sel_hi:[0,1]
	s_waitcnt lgkmcnt(0)
	v_pk_mul_f32 v[20:21], v[38:39], v[40:41] op_sel_hi:[0,1]
	v_pk_fma_f32 v[18:19], v[28:29], v[36:37], v[18:19] op_sel_hi:[1,0,1]
	v_pk_fma_f32 v[20:21], v[30:31], v[36:37], v[20:21] op_sel_hi:[1,0,1]
	s_waitcnt vmcnt(15)
	v_mov_b32_e32 v16, v198
	v_mov_b32_e32 v17, v199
	v_lshlrev_b32_e32 v22, 16, v16
	v_and_b32_e32 v23, 0xffff0000, v16
	v_lshlrev_b32_e32 v16, 16, v17
	v_and_b32_e32 v17, 0xffff0000, v17
	v_pk_mul_f32 v[18:19], v[18:19], v[22:23]
	v_pk_mul_f32 v[16:17], v[20:21], v[16:17]
	v_cvt_pk_bf16_f32 v18, v18, v19
	v_cvt_pk_bf16_f32 v19, v16, v17
	global_store_dwordx2 v[34:35], v[18:19], off offset:48
	ds_read2st64_b32 v[18:19], v82 offset0:48 offset1:49
	ds_read2st64_b32 v[20:21], v82 offset0:50 offset1:51
	ds_read2st64_b32 v[22:23], v82 offset0:52 offset1:53
	ds_read2st64_b32 v[24:25], v82 offset0:54 offset1:55
	s_waitcnt lgkmcnt(3)
	v_pk_mul_f32 v[18:19], v[38:39], v[18:19] op_sel_hi:[0,1]
	s_waitcnt lgkmcnt(2)
	v_pk_mul_f32 v[20:21], v[38:39], v[20:21] op_sel_hi:[0,1]
	v_pk_fma_f32 v[0:1], v[0:1], v[36:37], v[18:19] op_sel_hi:[1,0,1]
	v_pk_fma_f32 v[2:3], v[2:3], v[36:37], v[20:21] op_sel_hi:[1,0,1]
	s_waitcnt vmcnt(15)
	v_mov_b32_e32 v16, v200
	v_mov_b32_e32 v17, v201
	v_lshlrev_b32_e32 v18, 16, v16
	v_and_b32_e32 v19, 0xffff0000, v16
	v_lshlrev_b32_e32 v16, 16, v17
	v_and_b32_e32 v17, 0xffff0000, v17
	v_pk_mul_f32 v[0:1], v[0:1], v[18:19]
	v_pk_mul_f32 v[2:3], v[2:3], v[16:17]
	v_cvt_pk_bf16_f32 v0, v0, v1
	v_cvt_pk_bf16_f32 v1, v2, v3
	global_store_dwordx2 v[34:35], v[0:1], off offset:64
	s_waitcnt lgkmcnt(1)
	v_pk_mul_f32 v[2:3], v[38:39], v[22:23] op_sel_hi:[0,1]
	s_waitcnt lgkmcnt(0)
	v_pk_mul_f32 v[16:17], v[38:39], v[24:25] op_sel_hi:[0,1]
	v_pk_fma_f32 v[2:3], v[4:5], v[36:37], v[2:3] op_sel_hi:[1,0,1]
	v_pk_fma_f32 v[4:5], v[6:7], v[36:37], v[16:17] op_sel_hi:[1,0,1]
	s_waitcnt vmcnt(15)
	v_mov_b32_e32 v0, v202
	v_mov_b32_e32 v1, v203
	v_lshlrev_b32_e32 v6, 16, v0
	v_and_b32_e32 v7, 0xffff0000, v0
	v_lshlrev_b32_e32 v0, 16, v1
	v_and_b32_e32 v1, 0xffff0000, v1
	v_pk_mul_f32 v[2:3], v[2:3], v[6:7]
	v_pk_mul_f32 v[0:1], v[4:5], v[0:1]
	v_cvt_pk_bf16_f32 v2, v2, v3
	v_cvt_pk_bf16_f32 v3, v0, v1
	global_store_dwordx2 v[34:35], v[2:3], off offset:80
	ds_read2st64_b32 v[2:3], v82 offset0:56 offset1:57
	ds_read2st64_b32 v[4:5], v82 offset0:58 offset1:59
	ds_read2st64_b32 v[6:7], v82 offset0:60 offset1:61
	ds_read2st64_b32 v[16:17], v82 offset0:62 offset1:63
	s_waitcnt lgkmcnt(3)
	v_pk_mul_f32 v[2:3], v[38:39], v[2:3] op_sel_hi:[0,1]
	s_waitcnt lgkmcnt(2)
	v_pk_mul_f32 v[4:5], v[38:39], v[4:5] op_sel_hi:[0,1]
	v_pk_fma_f32 v[2:3], v[8:9], v[36:37], v[2:3] op_sel_hi:[1,0,1]
	v_pk_fma_f32 v[4:5], v[10:11], v[36:37], v[4:5] op_sel_hi:[1,0,1]
	s_waitcnt vmcnt(15)
	v_mov_b32_e32 v0, v204
	v_mov_b32_e32 v1, v205
	v_lshlrev_b32_e32 v8, 16, v0
	v_and_b32_e32 v9, 0xffff0000, v0
	v_lshlrev_b32_e32 v0, 16, v1
	v_and_b32_e32 v1, 0xffff0000, v1
	v_pk_mul_f32 v[2:3], v[2:3], v[8:9]
	v_pk_mul_f32 v[0:1], v[4:5], v[0:1]
	v_cvt_pk_bf16_f32 v2, v2, v3
	v_cvt_pk_bf16_f32 v3, v0, v1
	global_store_dwordx2 v[34:35], v[2:3], off offset:96
	s_waitcnt lgkmcnt(1)
	v_pk_mul_f32 v[2:3], v[38:39], v[6:7] op_sel_hi:[0,1]
	s_waitcnt lgkmcnt(0)
	v_pk_mul_f32 v[4:5], v[38:39], v[16:17] op_sel_hi:[0,1]
	v_pk_fma_f32 v[2:3], v[12:13], v[36:37], v[2:3] op_sel_hi:[1,0,1]
	v_pk_fma_f32 v[4:5], v[14:15], v[36:37], v[4:5] op_sel_hi:[1,0,1]
	s_waitcnt vmcnt(15)
	v_mov_b32_e32 v0, v206
	v_mov_b32_e32 v1, v207
	v_lshlrev_b32_e32 v6, 16, v0
	v_and_b32_e32 v7, 0xffff0000, v0
	v_lshlrev_b32_e32 v0, 16, v1
	v_and_b32_e32 v1, 0xffff0000, v1
	v_pk_mul_f32 v[2:3], v[2:3], v[6:7]
	v_pk_mul_f32 v[0:1], v[4:5], v[0:1]
	v_cvt_pk_bf16_f32 v2, v2, v3
	v_cvt_pk_bf16_f32 v3, v0, v1
	global_store_dwordx2 v[34:35], v[2:3], off offset:112
	s_branch .LBB0_1035
